# P1 norm tail: all 12 gamma/scale/shift loads issued up front with counted waits (was 4 dependent round trips per unit)
# baseline (speedup 1.0000x reference)
.LBB0_86:
	s_or_b64 exec, exec, s[0:1]
	v_mov_b32_e32 v37, s19
	ds_read_b64 v[64:65], v37
	v_add_co_u32_e32 v52, vcc, v52, v32
	v_addc_co_u32_e32 v53, vcc, v53, v33, vcc
	s_waitcnt lgkmcnt(0)
	global_load_dwordx4 v[42:45], v[52:53], off
	v_add_co_u32_e32 v48, vcc, v48, v32
	v_addc_co_u32_e32 v49, vcc, v49, v33, vcc
	global_load_dwordx4 v[68:71], v[48:49], off
	v_add_co_u32_e32 v72, vcc, v64, v32
	v_addc_co_u32_e32 v73, vcc, v65, v33, vcc
	global_load_dwordx4 v[64:67], v[72:73], off
	global_load_dwordx4 v[150:153], v[72:73], off offset:1024
	global_load_dwordx4 v[154:157], v[52:53], off offset:1024
	global_load_dwordx4 v[158:161], v[48:49], off offset:1024
	global_load_dwordx4 v[162:165], v[72:73], off offset:2048
	global_load_dwordx4 v[166:169], v[52:53], off offset:2048
	global_load_dwordx4 v[170:173], v[48:49], off offset:2048
	global_load_dwordx4 v[174:177], v[72:73], off offset:3072
	global_load_dwordx4 v[178:181], v[52:53], off offset:3072
	global_load_dwordx4 v[182:185], v[48:49], off offset:3072
	v_add_f32_e32 v37, v50, v35
	v_fmamk_f32 v39, v51, 0x3a800000, v55
	v_mul_f32_e32 v41, 0x4b800000, v39
	v_fmamk_f32 v37, v37, 0x3a800000, v55
	v_cmp_gt_f32_e32 vcc, s20, v39
	v_cmp_gt_f32_e64 s[0:1], s20, v37
	v_mov_b32_e32 v35, v33
	v_cndmask_b32_e32 v39, v39, v41, vcc
	v_mul_f32_e32 v41, 0x4b800000, v37
	v_rsq_f32_e32 v39, v39
	v_cndmask_b32_e64 v37, v37, v41, s[0:1]
	v_rsq_f32_e32 v37, v37
	v_lshl_add_u64 v[50:51], v[46:47], 0, v[34:35]
	v_mul_f32_e32 v35, 0x45800000, v39
	v_cndmask_b32_e32 v74, v39, v35, vcc
	v_mul_f32_e32 v35, 0x45800000, v37
	v_cndmask_b32_e64 v76, v37, v35, s[0:1]
	v_pk_mul_f32 v[24:25], v[24:25], v[74:75] op_sel_hi:[1,0]
	v_pk_mul_f32 v[26:27], v[26:27], v[74:75] op_sel_hi:[1,0]
	v_pk_mul_f32 v[28:29], v[28:29], v[76:77] op_sel_hi:[1,0]
	v_pk_mul_f32 v[30:31], v[30:31], v[76:77] op_sel_hi:[1,0]
	v_pk_mul_f32 v[12:13], v[12:13], v[74:75] op_sel_hi:[1,0]
	v_pk_mul_f32 v[14:15], v[14:15], v[74:75] op_sel_hi:[1,0]
	v_pk_mul_f32 v[20:21], v[20:21], v[76:77] op_sel_hi:[1,0]
	v_pk_mul_f32 v[22:23], v[22:23], v[76:77] op_sel_hi:[1,0]
	v_mov_b32_e32 v37, v33
	v_pk_mul_f32 v[8:9], v[8:9], v[74:75] op_sel_hi:[1,0]
	v_pk_mul_f32 v[10:11], v[10:11], v[74:75] op_sel_hi:[1,0]
	v_pk_mul_f32 v[16:17], v[16:17], v[76:77] op_sel_hi:[1,0]
	v_pk_mul_f32 v[18:19], v[18:19], v[76:77] op_sel_hi:[1,0]
	v_mov_b32_e32 v39, v33
	v_pk_mul_f32 v[0:1], v[0:1], v[74:75] op_sel_hi:[1,0]
	v_pk_mul_f32 v[2:3], v[2:3], v[74:75] op_sel_hi:[1,0]
	v_pk_mul_f32 v[4:5], v[4:5], v[76:77] op_sel_hi:[1,0]
	v_pk_mul_f32 v[6:7], v[6:7], v[76:77] op_sel_hi:[1,0]
	v_mov_b32_e32 v41, v33
	s_add_i32 s21, s21, s40
	s_add_i32 s3, s3, s14
	s_cmpk_gt_i32 s21, 0x87f
	s_waitcnt vmcnt(9) lgkmcnt(0)
	v_pk_add_f32 v[42:43], v[42:43], 1.0 op_sel_hi:[1,0]
	v_pk_add_f32 v[44:45], v[44:45], 1.0 op_sel_hi:[1,0]
	v_pk_mul_f32 v[24:25], v[64:65], v[24:25]
	v_pk_mul_f32 v[26:27], v[66:67], v[26:27]
	v_pk_mul_f32 v[28:29], v[64:65], v[28:29]
	v_pk_mul_f32 v[30:31], v[66:67], v[30:31]
	v_pk_fma_f32 v[24:25], v[24:25], v[42:43], v[68:69]
	v_pk_fma_f32 v[26:27], v[26:27], v[44:45], v[70:71]
	v_pk_fma_f32 v[28:29], v[42:43], v[28:29], v[68:69]
	v_pk_fma_f32 v[30:31], v[30:31], v[44:45], v[70:71]
	v_cvt_pk_bf16_f32 v24, v24, v25
	v_cvt_pk_bf16_f32 v25, v26, v27
	v_cvt_pk_bf16_f32 v26, v28, v29
	v_cvt_pk_bf16_f32 v27, v30, v31
	global_store_dwordx2 v[50:51], v[24:25], off
	global_store_dwordx2 v[50:51], v[26:27], off offset:2048
	v_lshl_add_u64 v[50:51], v[46:47], 0, v[36:37]
	s_waitcnt vmcnt(8)
	v_pk_mul_f32 v[12:13], v[12:13], v[150:151]
	v_pk_add_f32 v[154:155], v[154:155], 1.0 op_sel_hi:[1,0]
	v_pk_mul_f32 v[14:15], v[14:15], v[152:153]
	v_pk_add_f32 v[156:157], v[156:157], 1.0 op_sel_hi:[1,0]
	v_pk_mul_f32 v[20:21], v[20:21], v[150:151]
	v_pk_mul_f32 v[22:23], v[22:23], v[152:153]
	v_pk_fma_f32 v[12:13], v[12:13], v[154:155], v[158:159]
	v_pk_fma_f32 v[14:15], v[14:15], v[156:157], v[160:161]
	v_pk_fma_f32 v[20:21], v[20:21], v[154:155], v[158:159]
	v_pk_fma_f32 v[22:23], v[22:23], v[156:157], v[160:161]
	v_cvt_pk_bf16_f32 v12, v12, v13
	v_cvt_pk_bf16_f32 v13, v14, v15
	v_cvt_pk_bf16_f32 v14, v20, v21
	v_cvt_pk_bf16_f32 v15, v22, v23
	global_store_dwordx2 v[50:51], v[12:13], off
	global_store_dwordx2 v[50:51], v[14:15], off offset:2048
	v_lshl_add_u64 v[28:29], v[46:47], 0, v[38:39]
	s_waitcnt vmcnt(7)
	v_pk_mul_f32 v[8:9], v[8:9], v[162:163]
	v_pk_add_f32 v[166:167], v[166:167], 1.0 op_sel_hi:[1,0]
	v_pk_mul_f32 v[10:11], v[10:11], v[164:165]
	v_pk_add_f32 v[168:169], v[168:169], 1.0 op_sel_hi:[1,0]
	v_pk_mul_f32 v[16:17], v[16:17], v[162:163]
	v_pk_mul_f32 v[18:19], v[18:19], v[164:165]
	v_pk_fma_f32 v[8:9], v[8:9], v[166:167], v[170:171]
	v_pk_fma_f32 v[10:11], v[10:11], v[168:169], v[172:173]
	v_pk_fma_f32 v[16:17], v[16:17], v[166:167], v[170:171]
	v_pk_fma_f32 v[18:19], v[18:19], v[168:169], v[172:173]
	v_cvt_pk_bf16_f32 v8, v8, v9
	v_cvt_pk_bf16_f32 v9, v10, v11
	v_cvt_pk_bf16_f32 v10, v16, v17
	v_cvt_pk_bf16_f32 v11, v18, v19
	global_store_dwordx2 v[28:29], v[8:9], off
	global_store_dwordx2 v[28:29], v[10:11], off offset:2048
	v_lshl_add_u64 v[20:21], v[46:47], 0, v[40:41]
	s_waitcnt vmcnt(6)
	v_pk_mul_f32 v[0:1], v[0:1], v[174:175]
	v_pk_add_f32 v[178:179], v[178:179], 1.0 op_sel_hi:[1,0]
	v_pk_mul_f32 v[2:3], v[2:3], v[176:177]
	v_pk_add_f32 v[180:181], v[180:181], 1.0 op_sel_hi:[1,0]
	v_pk_mul_f32 v[4:5], v[4:5], v[174:175]
	v_pk_mul_f32 v[6:7], v[6:7], v[176:177]
	v_pk_fma_f32 v[0:1], v[0:1], v[178:179], v[182:183]
	v_pk_fma_f32 v[2:3], v[2:3], v[180:181], v[184:185]
	v_pk_fma_f32 v[4:5], v[4:5], v[178:179], v[182:183]
	v_pk_fma_f32 v[6:7], v[6:7], v[180:181], v[184:185]
	v_cvt_pk_bf16_f32 v0, v0, v1
	v_cvt_pk_bf16_f32 v1, v2, v3
	v_cvt_pk_bf16_f32 v2, v4, v5
	v_cvt_pk_bf16_f32 v3, v6, v7
	global_store_dwordx2 v[20:21], v[0:1], off
	global_store_dwordx2 v[20:21], v[2:3], off offset:2048
	s_cbranch_scc1 .LBB0_91
